# v25 + dropped m0 save/restore and pad nops around the 16 LDS-DMA issues of the GEMM main loop
# baseline (speedup 1.0000x reference)
; #define PG8_STAGE(bufoff, gbase, voff) do { _Pragma("unroll") for (int _i = 0; _i < 2; ++_i) \
;         pg8_dma16((const char*)(gbase), (voff)[_i], ldsb + (unsigned)((bufoff) + _i * 8192)); } while (0)
; #define PG8_LDA(dst, b, h) do { _Pragma("unroll") for (int m = 0; m < 4; ++m) _Pragma("unroll") for (int k = 0; k < 2; ++k) dst[m][k] = *(const PG8_LAS bf16x8*)(lds + PG8_SA(b, h) + aoff + m * 2048 + k * 1024); } while (0)
; #define PG8_LDB(dst, b, h) do { _Pragma("unroll") for (int n = 0; n < 2; ++n) _Pragma("unroll") for (int k = 0; k < 2; ++k) dst[n][k] = *(const PG8_LAS bf16x8*)(lds + PG8_SB(b, h) + boff + n * 2048 + k * 1024); } while (0)
; #define PG8_MMA(ai, bj, At, Bt) do { __builtin_amdgcn_s_setprio(1); _Pragma("unroll") for (int m = 0; m < 4; ++m) _Pragma("unroll") for (int n = 0; n < 2; ++n) _Pragma("unroll") for (int k = 0; k < 2; ++k) \
;         acc[ai][bj][m][n] = __builtin_amdgcn_mfma_f32_16x16x32_bf16(Bt[n][k], At[m][k], acc[ai][bj][m][n], 0, 0, 0); __builtin_amdgcn_s_setprio(0); } while (0)
; #define PG8_WAIT_V(n) asm volatile("s_waitcnt vmcnt(" #n ")" ::: "memory")
; #define PG8_WAIT_L(n) asm volatile("s_waitcnt lgkmcnt(" #n ")" ::: "memory")
; #define PG8_BAR __builtin_amdgcn_s_barrier()
; #define PG8_SCHED __builtin_amdgcn_sched_barrier(0)
; template <class Epi, class Sched, bool ALIGN_EPI = false, bool SP2 = false>
; __device__ __forceinline__ void gemm_phase(PG8_LAS unsigned char* lds, const Gemm g, const Sched& S, const Epi& E) {
;     ...
;             const bool last = (t == nt - 2);
;             const char* a1 = cA + (size_t)(t + 1) * kstep;
;             const char* a2 = last ? nA : cA + (size_t)(t + 2) * kstep; const char* b2 = last ? nB : cB + (size_t)(t + 2) * kstep;
;             const char* a3 = a2 + kstep; const char* b3 = b2 + kstep;
;             if (last && has_next) S.a_ready(nxt);
;             if constexpr (SP2) {
;             PG8_LDB(B0, 0, 0); PG8_LDB(B1, 0, 1); PG8_SCHED; PG8_LDA(At, 0, 0); PG8_STAGE(PG8_SA(1, 1), a1 + hstep, voffA);
;             PG8_WAIT_V(8); PG8_WAIT_L(0); PG8_BAR; PG8_MMA(0, 0, At, B0); PG8_MMA(0, 1, At, B1); PG8_BAR; PG8_SCHED;
;             PG8_LDA(At, 0, 1); PG8_STAGE(PG8_SB(0, 0), b2, voffB); PG8_STAGE(PG8_SB(0, 1), b2 + hstep, voffB); PG8_STAGE(PG8_SA(0, 0), a2, voffA);
;             PG8_WAIT_V(8); PG8_WAIT_L(0); PG8_BAR; PG8_MMA(1, 0, At, B0); PG8_MMA(1, 1, At, B1); PG8_BAR; PG8_SCHED;
.LBB0_305:
	v_add_u32_e32 v140, 0x10000, v207
	v_add_u32_e32 v160, 0x14000, v207
	ds_read_b128 v[128:131], v140
	ds_read_b128 v[132:135], v140 offset:1024
	ds_read_b128 v[136:139], v140 offset:2048
	ds_read_b128 v[140:143], v140 offset:3072
	ds_read_b128 v[144:147], v160
	ds_read_b128 v[152:155], v160 offset:1024
	ds_read_b128 v[156:159], v160 offset:2048
	ds_read_b128 v[160:163], v160 offset:3072
	s_add_i32 s58, s12, 2
	s_cmp_eq_u32 s77, s12
	s_cselect_b32 s40, s30, s72
	s_cselect_b32 s41, s31, s95
	s_cselect_b32 s36, s34, vcc_lo
	s_cselect_b32 s37, s35, vcc_hi
	s_add_u32 s12, s40, 0x80
	s_addc_u32 s13, s41, 0
	ds_read_b128 v[164:167], v208
	ds_read_b128 v[168:171], v208 offset:1024
	ds_read_b128 v[172:175], v208 offset:2048
	ds_read_b128 v[176:179], v208 offset:3072
	ds_read_b128 v[180:183], v208 offset:4096
	ds_read_b128 v[210:213], v208 offset:5120
	ds_read_b128 v[214:217], v208 offset:6144
	ds_read_b128 v[218:221], v208 offset:7168
	s_mov_b32 m0, s78
	s_nop 0
	global_load_lds_dwordx4 v148, s[10:11]
	s_mov_b32 m0, s80
	s_nop 0
	global_load_lds_dwordx4 v198, s[10:11]
	s_waitcnt vmcnt(8)
	s_waitcnt lgkmcnt(0)
	s_barrier
	s_setprio 1
	s_waitcnt lgkmcnt(7)
	v_mfma_f32_16x16x32_bf16 v[124:127], v[128:131], v[164:167], v[124:127]
	v_mfma_f32_16x16x32_bf16 v[116:119], v[136:139], v[164:167], v[116:119]
	s_waitcnt lgkmcnt(5)
	v_mfma_f32_16x16x32_bf16 v[108:111], v[128:131], v[172:175], v[108:111]
	v_mfma_f32_16x16x32_bf16 v[100:103], v[136:139], v[172:175], v[100:103]
	s_waitcnt lgkmcnt(3)
	v_mfma_f32_16x16x32_bf16 v[92:95], v[128:131], v[180:183], v[92:95]
	v_mfma_f32_16x16x32_bf16 v[84:87], v[136:139], v[180:183], v[84:87]
	s_waitcnt lgkmcnt(1)
	v_mfma_f32_16x16x32_bf16 v[76:79], v[128:131], v[214:217], v[76:79]
	v_mfma_f32_16x16x32_bf16 v[68:71], v[136:139], v[214:217], v[68:71]
	v_mfma_f32_16x16x32_bf16 v[124:127], v[132:135], v[168:171], v[124:127]
	v_mfma_f32_16x16x32_bf16 v[116:119], v[140:143], v[168:171], v[116:119]
	v_mfma_f32_16x16x32_bf16 v[108:111], v[132:135], v[176:179], v[108:111]
	v_mfma_f32_16x16x32_bf16 v[100:103], v[140:143], v[176:179], v[100:103]
	v_mfma_f32_16x16x32_bf16 v[92:95], v[132:135], v[210:213], v[92:95]
	v_mfma_f32_16x16x32_bf16 v[84:87], v[140:143], v[210:213], v[84:87]
	s_waitcnt lgkmcnt(0)
	v_mfma_f32_16x16x32_bf16 v[76:79], v[132:135], v[218:221], v[76:79]
	v_mfma_f32_16x16x32_bf16 v[68:71], v[140:143], v[218:221], v[68:71]
	s_setprio 0
	s_setprio 1
	v_mfma_f32_16x16x32_bf16 v[120:123], v[144:147], v[164:167], v[120:123]
	v_mfma_f32_16x16x32_bf16 v[112:115], v[156:159], v[164:167], v[112:115]
	v_mfma_f32_16x16x32_bf16 v[104:107], v[144:147], v[172:175], v[104:107]
	v_mfma_f32_16x16x32_bf16 v[96:99], v[156:159], v[172:175], v[96:99]
	v_mfma_f32_16x16x32_bf16 v[88:91], v[144:147], v[180:183], v[88:91]
	v_mfma_f32_16x16x32_bf16 v[80:83], v[156:159], v[180:183], v[80:83]
	v_mfma_f32_16x16x32_bf16 v[72:75], v[144:147], v[214:217], v[72:75]
	v_mfma_f32_16x16x32_bf16 v[64:67], v[156:159], v[214:217], v[64:67]
	v_mfma_f32_16x16x32_bf16 v[120:123], v[152:155], v[168:171], v[120:123]
	v_mfma_f32_16x16x32_bf16 v[112:115], v[160:163], v[168:171], v[112:115]
	v_mfma_f32_16x16x32_bf16 v[104:107], v[152:155], v[176:179], v[104:107]
	v_mfma_f32_16x16x32_bf16 v[96:99], v[160:163], v[176:179], v[96:99]
	v_mfma_f32_16x16x32_bf16 v[88:91], v[152:155], v[210:213], v[88:91]
	v_mfma_f32_16x16x32_bf16 v[80:83], v[160:163], v[210:213], v[80:83]
	v_mfma_f32_16x16x32_bf16 v[72:75], v[152:155], v[218:221], v[72:75]
	v_mfma_f32_16x16x32_bf16 v[64:67], v[160:163], v[218:221], v[64:67]
	s_setprio 0
	s_barrier
	ds_read_b128 v[164:167], v208 offset:16384
	ds_read_b128 v[168:171], v208 offset:17408
	ds_read_b128 v[172:175], v208 offset:18432
	ds_read_b128 v[176:179], v208 offset:19456
	ds_read_b128 v[180:183], v208 offset:20480
	ds_read_b128 v[210:213], v208 offset:21504
	ds_read_b128 v[214:217], v208 offset:22528
	ds_read_b128 v[218:221], v208 offset:23552
	s_mov_b32 m0, s50
	s_nop 0
	global_load_lds_dwordx4 v151, s[36:37]
	s_mov_b32 m0, s51
	s_nop 0
	global_load_lds_dwordx4 v199, s[36:37]
	s_add_u32 s4, s36, s47
	s_addc_u32 s5, s37, 0
	s_mov_b32 m0, s61
	s_nop 0
	global_load_lds_dwordx4 v151, s[4:5]
	s_mov_b32 m0, s62
	s_nop 0
	global_load_lds_dwordx4 v199, s[4:5]
	s_mov_b32 m0, s49
	s_nop 0
	global_load_lds_dwordx4 v148, s[40:41]
	s_mov_b32 m0, s63
	s_nop 0
	global_load_lds_dwordx4 v198, s[40:41]
	s_waitcnt vmcnt(8)
	s_waitcnt lgkmcnt(0)
	s_barrier
	s_setprio 1
	s_waitcnt lgkmcnt(7)
	v_mfma_f32_16x16x32_bf16 v[60:63], v[128:131], v[164:167], v[60:63]
	v_mfma_f32_16x16x32_bf16 v[52:55], v[136:139], v[164:167], v[52:55]
	s_waitcnt lgkmcnt(5)
	v_mfma_f32_16x16x32_bf16 v[44:47], v[128:131], v[172:175], v[44:47]
	v_mfma_f32_16x16x32_bf16 v[36:39], v[136:139], v[172:175], v[36:39]
	s_waitcnt lgkmcnt(3)
	v_mfma_f32_16x16x32_bf16 v[28:31], v[128:131], v[180:183], v[28:31]
	v_mfma_f32_16x16x32_bf16 v[20:23], v[136:139], v[180:183], v[20:23]
	s_waitcnt lgkmcnt(1)
	v_mfma_f32_16x16x32_bf16 v[12:15], v[128:131], v[214:217], v[12:15]
	v_mfma_f32_16x16x32_bf16 v[4:7], v[136:139], v[214:217], v[4:7]
	v_mfma_f32_16x16x32_bf16 v[60:63], v[132:135], v[168:171], v[60:63]
	v_mfma_f32_16x16x32_bf16 v[52:55], v[140:143], v[168:171], v[52:55]
	v_mfma_f32_16x16x32_bf16 v[44:47], v[132:135], v[176:179], v[44:47]
	v_mfma_f32_16x16x32_bf16 v[36:39], v[140:143], v[176:179], v[36:39]
	v_mfma_f32_16x16x32_bf16 v[28:31], v[132:135], v[210:213], v[28:31]
	v_mfma_f32_16x16x32_bf16 v[20:23], v[140:143], v[210:213], v[20:23]
	s_waitcnt lgkmcnt(0)
	v_mfma_f32_16x16x32_bf16 v[12:15], v[132:135], v[218:221], v[12:15]
	v_mfma_f32_16x16x32_bf16 v[4:7], v[140:143], v[218:221], v[4:7]
	s_setprio 0
	s_setprio 1
	v_mfma_f32_16x16x32_bf16 v[56:59], v[144:147], v[164:167], v[56:59]
	v_mfma_f32_16x16x32_bf16 v[48:51], v[156:159], v[164:167], v[48:51]
	v_mfma_f32_16x16x32_bf16 v[40:43], v[144:147], v[172:175], v[40:43]
	v_mfma_f32_16x16x32_bf16 v[32:35], v[156:159], v[172:175], v[32:35]
	v_mfma_f32_16x16x32_bf16 v[24:27], v[144:147], v[180:183], v[24:27]
	v_mfma_f32_16x16x32_bf16 v[16:19], v[156:159], v[180:183], v[16:19]
	v_mfma_f32_16x16x32_bf16 v[8:11], v[144:147], v[214:217], v[8:11]
	v_mfma_f32_16x16x32_bf16 v[0:3], v[156:159], v[214:217], v[0:3]
	v_mfma_f32_16x16x32_bf16 v[56:59], v[152:155], v[168:171], v[56:59]
	v_mfma_f32_16x16x32_bf16 v[48:51], v[160:163], v[168:171], v[48:51]
	v_mfma_f32_16x16x32_bf16 v[40:43], v[152:155], v[176:179], v[40:43]
	v_mfma_f32_16x16x32_bf16 v[32:35], v[160:163], v[176:179], v[32:35]
	v_mfma_f32_16x16x32_bf16 v[24:27], v[152:155], v[210:213], v[24:27]
	v_mfma_f32_16x16x32_bf16 v[16:19], v[160:163], v[210:213], v[16:19]
	v_mfma_f32_16x16x32_bf16 v[8:11], v[152:155], v[218:221], v[8:11]
	v_mfma_f32_16x16x32_bf16 v[0:3], v[160:163], v[218:221], v[0:3]
	s_setprio 0
	s_barrier
; #define PG8_STAGE(bufoff, gbase, voff) do { _Pragma("unroll") for (int _i = 0; _i < 2; ++_i) \
;         pg8_dma16((const char*)(gbase), (voff)[_i], ldsb + (unsigned)((bufoff) + _i * 8192)); } while (0)
; #define PG8_LDA(dst, b, h) do { _Pragma("unroll") for (int m = 0; m < 4; ++m) _Pragma("unroll") for (int k = 0; k < 2; ++k) dst[m][k] = *(const PG8_LAS bf16x8*)(lds + PG8_SA(b, h) + aoff + m * 2048 + k * 1024); } while (0)
; #define PG8_LDB(dst, b, h) do { _Pragma("unroll") for (int n = 0; n < 2; ++n) _Pragma("unroll") for (int k = 0; k < 2; ++k) dst[n][k] = *(const PG8_LAS bf16x8*)(lds + PG8_SB(b, h) + boff + n * 2048 + k * 1024); } while (0)
; #define PG8_MMA(ai, bj, At, Bt) do { __builtin_amdgcn_s_setprio(1); _Pragma("unroll") for (int m = 0; m < 4; ++m) _Pragma("unroll") for (int n = 0; n < 2; ++n) _Pragma("unroll") for (int k = 0; k < 2; ++k) \
;         acc[ai][bj][m][n] = __builtin_amdgcn_mfma_f32_16x16x32_bf16(Bt[n][k], At[m][k], acc[ai][bj][m][n], 0, 0, 0); __builtin_amdgcn_s_setprio(0); } while (0)
; #define PG8_WAIT_V(n) asm volatile("s_waitcnt vmcnt(" #n ")" ::: "memory")
; #define PG8_WAIT_L(n) asm volatile("s_waitcnt lgkmcnt(" #n ")" ::: "memory")
; #define PG8_BAR __builtin_amdgcn_s_barrier()
; #define PG8_SCHED __builtin_amdgcn_sched_barrier(0)
; template <class Epi, class Sched, bool ALIGN_EPI = false, bool SP2 = false>
; __device__ __forceinline__ void gemm_phase(PG8_LAS unsigned char* lds, const Gemm g, const Sched& S, const Epi& E) {
;     ...
;             PG8_LDB(B0, 1, 0); PG8_LDB(B1, 1, 1); PG8_SCHED; PG8_LDA(At, 1, 0); PG8_STAGE(PG8_SA(0, 1), a2 + hstep, voffA);
;             PG8_WAIT_V(8); PG8_WAIT_L(0); PG8_BAR; PG8_MMA(0, 0, At, B0); PG8_MMA(0, 1, At, B1); PG8_BAR; PG8_SCHED;
	v_add_u32_e32 v140, 0x18000, v207
	v_add_u32_e32 v160, 0x1c000, v207
	ds_read_b128 v[128:131], v140
	ds_read_b128 v[132:135], v140 offset:1024
	ds_read_b128 v[136:139], v140 offset:2048
	ds_read_b128 v[140:143], v140 offset:3072
	ds_read_b128 v[144:147], v160
	ds_read_b128 v[152:155], v160 offset:1024
	ds_read_b128 v[156:159], v160 offset:2048
	ds_read_b128 v[160:163], v160 offset:3072
	ds_read_b128 v[164:167], v208 offset:32768
	ds_read_b128 v[168:171], v208 offset:33792
	ds_read_b128 v[172:175], v208 offset:34816
	ds_read_b128 v[176:179], v208 offset:35840
	ds_read_b128 v[180:183], v208 offset:36864
	ds_read_b128 v[210:213], v208 offset:37888
	ds_read_b128 v[214:217], v208 offset:38912
	ds_read_b128 v[218:221], v208 offset:39936
	s_add_u32 s4, s40, s47
	s_addc_u32 s5, s41, 0
	s_mov_b32 m0, s64
	s_nop 0
	global_load_lds_dwordx4 v148, s[4:5]
	s_mov_b32 m0, s65
	s_nop 0
	global_load_lds_dwordx4 v198, s[4:5]
	s_waitcnt vmcnt(8)
	s_waitcnt lgkmcnt(0)
	s_barrier
	s_setprio 1
	s_waitcnt lgkmcnt(7)
	v_mfma_f32_16x16x32_bf16 v[124:127], v[128:131], v[164:167], v[124:127]
	v_mfma_f32_16x16x32_bf16 v[116:119], v[136:139], v[164:167], v[116:119]
	s_waitcnt lgkmcnt(5)
	v_mfma_f32_16x16x32_bf16 v[108:111], v[128:131], v[172:175], v[108:111]
	v_mfma_f32_16x16x32_bf16 v[100:103], v[136:139], v[172:175], v[100:103]
	s_waitcnt lgkmcnt(3)
	v_mfma_f32_16x16x32_bf16 v[92:95], v[128:131], v[180:183], v[92:95]
	v_mfma_f32_16x16x32_bf16 v[84:87], v[136:139], v[180:183], v[84:87]
	s_waitcnt lgkmcnt(1)
	v_mfma_f32_16x16x32_bf16 v[76:79], v[128:131], v[214:217], v[76:79]
	v_mfma_f32_16x16x32_bf16 v[68:71], v[136:139], v[214:217], v[68:71]
	v_mfma_f32_16x16x32_bf16 v[124:127], v[132:135], v[168:171], v[124:127]
	v_mfma_f32_16x16x32_bf16 v[116:119], v[140:143], v[168:171], v[116:119]
	v_mfma_f32_16x16x32_bf16 v[108:111], v[132:135], v[176:179], v[108:111]
	v_mfma_f32_16x16x32_bf16 v[100:103], v[140:143], v[176:179], v[100:103]
	v_mfma_f32_16x16x32_bf16 v[92:95], v[132:135], v[210:213], v[92:95]
	v_mfma_f32_16x16x32_bf16 v[84:87], v[140:143], v[210:213], v[84:87]
	s_waitcnt lgkmcnt(0)
	v_mfma_f32_16x16x32_bf16 v[76:79], v[132:135], v[218:221], v[76:79]
	v_mfma_f32_16x16x32_bf16 v[68:71], v[140:143], v[218:221], v[68:71]
	s_setprio 0
	s_setprio 1
	v_mfma_f32_16x16x32_bf16 v[120:123], v[144:147], v[164:167], v[120:123]
	v_mfma_f32_16x16x32_bf16 v[112:115], v[156:159], v[164:167], v[112:115]
	v_mfma_f32_16x16x32_bf16 v[104:107], v[144:147], v[172:175], v[104:107]
	v_mfma_f32_16x16x32_bf16 v[96:99], v[156:159], v[172:175], v[96:99]
	v_mfma_f32_16x16x32_bf16 v[88:91], v[144:147], v[180:183], v[88:91]
	v_mfma_f32_16x16x32_bf16 v[80:83], v[156:159], v[180:183], v[80:83]
	v_mfma_f32_16x16x32_bf16 v[72:75], v[144:147], v[214:217], v[72:75]
	v_mfma_f32_16x16x32_bf16 v[64:67], v[156:159], v[214:217], v[64:67]
	v_mfma_f32_16x16x32_bf16 v[120:123], v[152:155], v[168:171], v[120:123]
	v_mfma_f32_16x16x32_bf16 v[112:115], v[160:163], v[168:171], v[112:115]
	v_mfma_f32_16x16x32_bf16 v[104:107], v[152:155], v[176:179], v[104:107]
	v_mfma_f32_16x16x32_bf16 v[96:99], v[160:163], v[176:179], v[96:99]
	v_mfma_f32_16x16x32_bf16 v[88:91], v[152:155], v[210:213], v[88:91]
	v_mfma_f32_16x16x32_bf16 v[80:83], v[160:163], v[210:213], v[80:83]
	v_mfma_f32_16x16x32_bf16 v[72:75], v[152:155], v[218:221], v[72:75]
	v_mfma_f32_16x16x32_bf16 v[64:67], v[160:163], v[218:221], v[64:67]
	s_setprio 0
	s_barrier
; #define PG8_STAGE(bufoff, gbase, voff) do { _Pragma("unroll") for (int _i = 0; _i < 2; ++_i) \
;         pg8_dma16((const char*)(gbase), (voff)[_i], ldsb + (unsigned)((bufoff) + _i * 8192)); } while (0)
; #define PG8_LDA(dst, b, h) do { _Pragma("unroll") for (int m = 0; m < 4; ++m) _Pragma("unroll") for (int k = 0; k < 2; ++k) dst[m][k] = *(const PG8_LAS bf16x8*)(lds + PG8_SA(b, h) + aoff + m * 2048 + k * 1024); } while (0)
; #define PG8_MMA(ai, bj, At, Bt) do { __builtin_amdgcn_s_setprio(1); _Pragma("unroll") for (int m = 0; m < 4; ++m) _Pragma("unroll") for (int n = 0; n < 2; ++n) _Pragma("unroll") for (int k = 0; k < 2; ++k) \
;         acc[ai][bj][m][n] = __builtin_amdgcn_mfma_f32_16x16x32_bf16(Bt[n][k], At[m][k], acc[ai][bj][m][n], 0, 0, 0); __builtin_amdgcn_s_setprio(0); } while (0)
; #define PG8_WAIT_V(n) asm volatile("s_waitcnt vmcnt(" #n ")" ::: "memory")
; #define PG8_WAIT_L(n) asm volatile("s_waitcnt lgkmcnt(" #n ")" ::: "memory")
; #define PG8_BAR __builtin_amdgcn_s_barrier()
; #define PG8_SCHED __builtin_amdgcn_sched_barrier(0)
; template <class Epi, class Sched, bool ALIGN_EPI = false, bool SP2 = false>
; __device__ __forceinline__ void gemm_phase(PG8_LAS unsigned char* lds, const Gemm g, const Sched& S, const Epi& E) {
;     ...
;             PG8_LDA(At, 1, 1); PG8_STAGE(PG8_SB(1, 0), b3, voffB); PG8_STAGE(PG8_SB(1, 1), b3 + hstep, voffB); PG8_STAGE(PG8_SA(1, 0), a3, voffA);
;             PG8_WAIT_V(8); PG8_WAIT_L(0); PG8_BAR; PG8_MMA(1, 0, At, B0); PG8_MMA(1, 1, At, B1); PG8_BAR; PG8_SCHED;
;     ...
;         if constexpr (ALIGN_EPI) { if (wr == 0) PG8_BAR; }
	ds_read_b128 v[164:167], v208 offset:49152
	ds_read_b128 v[168:171], v208 offset:50176
	ds_read_b128 v[172:175], v208 offset:51200
	ds_read_b128 v[176:179], v208 offset:52224
	ds_read_b128 v[180:183], v208 offset:53248
	ds_read_b128 v[210:213], v208 offset:54272
	ds_read_b128 v[214:217], v208 offset:55296
	ds_read_b128 v[218:221], v208 offset:56320
	s_add_u32 s4, s36, 0x80
	s_addc_u32 s5, s37, 0
	s_mov_b32 m0, s67
	s_nop 0
	global_load_lds_dwordx4 v151, s[4:5]
	s_mov_b32 m0, s70
	s_nop 0
	global_load_lds_dwordx4 v199, s[4:5]
	s_add_u32 s4, s4, s47
	s_addc_u32 s5, s5, 0
	s_mov_b32 m0, s75
	s_nop 0
	global_load_lds_dwordx4 v151, s[4:5]
	s_mov_b32 m0, s76
	s_nop 0
	global_load_lds_dwordx4 v199, s[4:5]
	s_mov_b32 m0, s71
	s_nop 0
	global_load_lds_dwordx4 v148, s[12:13]
	s_mov_b32 m0, s74
	s_nop 0
	global_load_lds_dwordx4 v198, s[12:13]
	s_add_u32 s72, s72, 0x100
	s_addc_u32 s95, s95, 0
	s_add_u32 vcc_lo, vcc_lo, 0x100
	s_addc_u32 vcc_hi, vcc_hi, 0
	s_add_u32 s10, s10, 0x100
	s_addc_u32 s11, s11, 0
	s_mov_b32 s12, s58
	s_cmp_ge_u32 s58, s60
	s_waitcnt vmcnt(8)
	s_waitcnt lgkmcnt(0)
	s_barrier
	s_setprio 1
	s_waitcnt lgkmcnt(7)
	v_mfma_f32_16x16x32_bf16 v[60:63], v[128:131], v[164:167], v[60:63]
	v_mfma_f32_16x16x32_bf16 v[52:55], v[136:139], v[164:167], v[52:55]
	s_waitcnt lgkmcnt(5)
	v_mfma_f32_16x16x32_bf16 v[44:47], v[128:131], v[172:175], v[44:47]
	v_mfma_f32_16x16x32_bf16 v[36:39], v[136:139], v[172:175], v[36:39]
	s_waitcnt lgkmcnt(3)
	v_mfma_f32_16x16x32_bf16 v[28:31], v[128:131], v[180:183], v[28:31]
	v_mfma_f32_16x16x32_bf16 v[20:23], v[136:139], v[180:183], v[20:23]
	s_waitcnt lgkmcnt(1)
	v_mfma_f32_16x16x32_bf16 v[12:15], v[128:131], v[214:217], v[12:15]
	v_mfma_f32_16x16x32_bf16 v[4:7], v[136:139], v[214:217], v[4:7]
	v_mfma_f32_16x16x32_bf16 v[60:63], v[132:135], v[168:171], v[60:63]
	v_mfma_f32_16x16x32_bf16 v[52:55], v[140:143], v[168:171], v[52:55]
	v_mfma_f32_16x16x32_bf16 v[44:47], v[132:135], v[176:179], v[44:47]
	v_mfma_f32_16x16x32_bf16 v[36:39], v[140:143], v[176:179], v[36:39]
	v_mfma_f32_16x16x32_bf16 v[28:31], v[132:135], v[210:213], v[28:31]
	v_mfma_f32_16x16x32_bf16 v[20:23], v[140:143], v[210:213], v[20:23]
	s_waitcnt lgkmcnt(0)
	v_mfma_f32_16x16x32_bf16 v[12:15], v[132:135], v[218:221], v[12:15]
	v_mfma_f32_16x16x32_bf16 v[4:7], v[140:143], v[218:221], v[4:7]
	s_setprio 0
	s_setprio 1
	v_mfma_f32_16x16x32_bf16 v[56:59], v[144:147], v[164:167], v[56:59]
	v_mfma_f32_16x16x32_bf16 v[48:51], v[156:159], v[164:167], v[48:51]
	v_mfma_f32_16x16x32_bf16 v[40:43], v[144:147], v[172:175], v[40:43]
	v_mfma_f32_16x16x32_bf16 v[32:35], v[156:159], v[172:175], v[32:35]
	v_mfma_f32_16x16x32_bf16 v[24:27], v[144:147], v[180:183], v[24:27]
	v_mfma_f32_16x16x32_bf16 v[16:19], v[156:159], v[180:183], v[16:19]
	v_mfma_f32_16x16x32_bf16 v[8:11], v[144:147], v[214:217], v[8:11]
	v_mfma_f32_16x16x32_bf16 v[0:3], v[156:159], v[214:217], v[0:3]
	v_mfma_f32_16x16x32_bf16 v[56:59], v[152:155], v[168:171], v[56:59]
	v_mfma_f32_16x16x32_bf16 v[48:51], v[160:163], v[168:171], v[48:51]
	v_mfma_f32_16x16x32_bf16 v[40:43], v[152:155], v[176:179], v[40:43]
	v_mfma_f32_16x16x32_bf16 v[32:35], v[160:163], v[176:179], v[32:35]
	v_mfma_f32_16x16x32_bf16 v[24:27], v[152:155], v[210:213], v[24:27]
	v_mfma_f32_16x16x32_bf16 v[16:19], v[160:163], v[210:213], v[16:19]
	v_mfma_f32_16x16x32_bf16 v[8:11], v[152:155], v[218:221], v[8:11]
	v_mfma_f32_16x16x32_bf16 v[0:3], v[160:163], v[218:221], v[0:3]
	s_setprio 0
	s_barrier
	s_cbranch_scc0 .LBB0_305
	s_and_b64 vcc, exec, s[24:25]
	s_cbranch_vccz .LBB0_309
	s_barrier
	s_lshl_b32 s40, s94, 8
	s_cmp_lt_i32 s93, 2
	s_mov_b64 s[10:11], -1
	s_cbranch_scc0 .LBB0_310
